# speedup vs baseline: 1.0261x; 1.0023x over previous
; template <bool ATRANS = false, bool SWAP = true>
; DEV void gemm_seg(f32x4 (&acc)[4][4], bf16_t* As, bf16_t* Bs, const bf16_t* A, const bf16_t* B, int lda, int ldb,
;                   int K, int arow_lo, int arow_hi) {
;   const int tid = TID(), lane = tid & 63, wid = tid >> 6, wr = wid >> 1, wc = wid & 1;
;   const int fr = lane & 15, fq = lane >> 4;
;   const int lrow = tid >> 3, lk = (tid & 7) * 8;
;   const int tk = tid >> 4, trg = (tid & 15) * 8;
;   const bool av0 = (lrow >= arow_lo) && (lrow < arow_hi), av1 = (lrow + 32 >= arow_lo) && (lrow + 32 < arow_hi),
;              av2 = (lrow + 64 >= arow_lo) && (lrow + 64 < arow_hi), av3 = (lrow + 96 >= arow_lo) && (lrow + 96 < arow_hi);
;   const int c0 = min(max(lrow, arow_lo), arow_hi - 1), c1 = min(max(lrow + 32, arow_lo), arow_hi - 1),
;             c2 = min(max(lrow + 64, arow_lo), arow_hi - 1), c3 = min(max(lrow + 96, arow_lo), arow_hi - 1);
;   const bf16_t* a0 = ATRANS ? A + (long)(tk) * lda + trg : A + (long)c0 * lda + lk;
;   const bf16_t* a1 = ATRANS ? A + (long)(tk + 16) * lda + trg : A + (long)c1 * lda + lk;
;   const bf16_t* a2 = ATRANS ? A + (long)(tk + 32) * lda + trg : A + (long)c2 * lda + lk;
;   const bf16_t* a3 = ATRANS ? A + (long)(tk + 48) * lda + trg : A + (long)c3 * lda + lk;
;   const bf16_t* b0 = B + (long)lrow * ldb + lk;
;   const long bstep = 32L * ldb;
;   const long astep = ATRANS ? (long)lda : 1L;
;   uint4 A0a, A0b, A0c, A0d, B0a, B0b, B0c, B0d;
;   uint4 A1a, A1b, A1c, A1d, B1a, B1b, B1c, B1d;
;   const int so = lrow * LDT + lk;
;   const int sw = lrow * 64 + (((lk >> 3) ^ (lrow & 7)) * 8);
;   const int nk = K / BK;
;   const unsigned am0 = av0 ? 0xffffffffu : 0u, am1 = av1 ? 0xffffffffu : 0u, am2 = av2 ? 0xffffffffu : 0u,
;                  am3 = av3 ? 0xffffffffu : 0u;
; DEV void phase_up(const Params& p, int layer, char* smem) {
;     ...
;   for (int it = BID(); it < ntiles; it += NBLK()) {
;     const int tid = TID(), lane = tid & 63, wid = tid >> 6;
;     const int tn = it % 44, tmm = it / 44;
;     const int sl = tmm / MT, tm = tmm % MT;
;     const int tstart = 126 * tm - 1;
;     const int lo = max(0, -tstart), hi = min(128, L - tstart);
;     gemm_tile1<true>(smem, p.Hwk + ((long)sl * L + tstart) * D, p.WupT + (long)layer * 2 * DFF * D + (long)tn * 128 * D,
;                      D, D, D, lo, hi);
.LBB0_821:
	s_cmpk_gt_i32 s20, 0x38b7
	s_cbranch_scc1 .LBB0_838
	s_lshr_b32 s0, s20, 3
	s_mul_i32 s1, s0, 0x1746
	s_lshr_b32 s1, s1, 16
	s_mul_i32 s2, s1, 11
	s_sub_i32 s0, s0, s2
	s_mul_i32 s1, s1, 88
	s_add_i32 s0, s0, s1
	s_and_b32 s1, s20, 3
	s_mul_i32 s1, s1, 11
	s_add_i32 s0, s0, s1
	s_bfe_u32 s1, s20, 0x10002
	s_mul_i32 s1, s1, 44
	s_add_i32 s2, s0, s1
	s_mul_hi_i32 s0, s2, 0x2e8ba2e9
	s_lshr_b32 s1, s0, 31
	s_ashr_i32 s0, s0, 3
	s_add_i32 s1, s0, s1
	s_mul_i32 s0, s1, 44
	s_sub_i32 s60, s2, s0
	s_mul_hi_i32 s0, s2, 0xb48a39d5
	s_add_i32 s0, s0, s2
	s_lshr_b32 s2, s0, 31
	s_ashr_i32 s0, s0, 10
	s_add_i32 s0, s0, s2
	s_mul_hi_i32 s2, s1, 0x3e0f83e1
	s_lshr_b32 s3, s2, 31
	s_ashr_i32 s2, s2, 3
	s_add_i32 s2, s2, s3
	s_mul_i32 s2, s2, 33
	s_sub_i32 s1, s1, s2
	s_mul_i32 s34, s1, 0x7e
	s_sub_i32 s1, 1, s34
	s_max_i32 s8, s1, 0
	s_sub_i32 s1, 0x1001, s34
	s_add_i32 s21, s34, -1
	s_min_u32 s9, s1, 0x80
	s_ashr_i32 s1, s0, 31
	s_lshl_b64 s[18:19], s[0:1], 12
	s_ashr_i32 s3, s21, 31
	s_add_u32 s2, s18, s21
	s_addc_u32 s3, s19, s3
	s_lshl_b64 s[2:3], s[2:3], 11
	s_add_u32 s2, s72, s2
	v_mov_b32_e32 v133, v166
	s_addc_u32 s3, s73, s3
	s_ashr_i32 s61, s60, 31
	v_mov_b32_e32 v90, v166
	s_lshl_b64 s[4:5], s[60:61], 18
	v_readlane_b32 s6, v255, 24
	s_add_u32 s4, s6, s4
	v_ashrrev_i32_e32 v64, 3, v90
	v_readlane_b32 s6, v255, 25
	v_add_u32_e32 v9, 64, v64
	s_addc_u32 s5, s6, s5
	v_add_u32_e32 v10, 0x60, v64
	s_add_i32 s6, s9, -1
	v_max_i32_e32 v1, s8, v9
	v_add_u32_e32 v8, 32, v64
	v_max_i32_e32 v0, s8, v64
	v_min_u32_e32 v2, s6, v1
	v_max_i32_e32 v1, s8, v10
	v_min_u32_e32 v128, s6, v0
	v_max_i32_e32 v0, s8, v8
	v_min_u32_e32 v4, s6, v1
	v_lshlrev_b32_e32 v1, 4, v90
	v_min_u32_e32 v0, s6, v0
	v_lshlrev_b64 v[66:67], 11, v[128:129]
	v_and_b32_e32 v128, 0x70, v1
	v_mov_b32_e32 v1, v129
	v_lshlrev_b64 v[70:71], 11, v[0:1]
	v_mov_b32_e32 v3, v129
	v_lshl_add_u64 v[0:1], s[2:3], 0, v[70:71]
	v_lshlrev_b64 v[74:75], 11, v[2:3]
	v_mov_b32_e32 v5, v129
	v_lshl_add_u64 v[72:73], v[0:1], 0, v[128:129]
	v_lshl_add_u64 v[0:1], s[2:3], 0, v[74:75]
	v_lshlrev_b64 v[78:79], 11, v[4:5]
	v_lshl_add_u64 v[76:77], v[0:1], 0, v[128:129]
	v_lshl_add_u64 v[0:1], s[2:3], 0, v[78:79]
	v_ashrrev_i32_e32 v65, 31, v64
	v_lshl_add_u64 v[80:81], v[0:1], 0, v[128:129]
	v_lshlrev_b64 v[0:1], 11, v[64:65]
	v_lshl_add_u64 v[144:145], s[4:5], 0, v[0:1]
	v_lshl_add_u64 v[6:7], s[2:3], 0, v[66:67]
	v_lshl_add_u64 v[82:83], v[144:145], 0, v[128:129]
	s_mov_b32 s2, 0x10000
	v_add_co_u32_e32 v84, vcc, s2, v82
	s_mov_b32 s2, 0x20000
	s_nop 0
	v_addc_co_u32_e32 v85, vcc, 0, v83, vcc
	v_lshl_add_u64 v[68:69], v[6:7], 0, v[128:129]
	v_add_co_u32_e32 v86, vcc, s2, v82
	global_load_dwordx4 v[28:31], v[68:69], off
	global_load_dwordx4 v[36:39], v[72:73], off
	global_load_dwordx4 v[40:43], v[76:77], off
	global_load_dwordx4 v[44:47], v[80:81], off
	v_addc_co_u32_e32 v87, vcc, 0, v83, vcc
	s_mov_b32 s2, 0x30000
	v_add_co_u32_e32 v88, vcc, s2, v82
	global_load_dwordx4 v[48:51], v[82:83], off
	global_load_dwordx4 v[52:55], v[84:85], off
	v_addc_co_u32_e32 v89, vcc, 0, v83, vcc
	global_load_dwordx4 v[56:59], v[86:87], off
	global_load_dwordx4 v[60:63], v[88:89], off
	v_cmp_le_i32_e32 vcc, s8, v64
	v_cmp_gt_i32_e64 s[2:3], s9, v64
	s_and_b64 s[2:3], vcc, s[2:3]
	v_cmp_le_i32_e32 vcc, s8, v8
	v_cmp_gt_i32_e64 s[4:5], s9, v8
	s_and_b64 s[4:5], vcc, s[4:5]
	v_cmp_le_i32_e32 vcc, s8, v9
	v_cmp_gt_i32_e64 s[6:7], s9, v9
	v_lshlrev_b32_e32 v0, 3, v90
	s_and_b64 s[6:7], vcc, s[6:7]
	v_cmp_le_i32_e32 vcc, s8, v10
	v_cmp_gt_i32_e64 s[8:9], s9, v10
	v_lshrrev_b32_e32 v65, 4, v90
	v_bfe_u32 v91, v90, 4, 2
	s_and_b64 s[8:9], vcc, s[8:9]
	v_bitop3_b32 v92, v0, 56, v90 bitop3:0x48
	global_load_dwordx4 v[0:3], v[68:69], off offset:128
	global_load_dwordx4 v[4:7], v[72:73], off offset:128
	global_load_dwordx4 v[8:11], v[76:77], off offset:128
	global_load_dwordx4 v[12:15], v[80:81], off offset:128
	global_load_dwordx4 v[16:19], v[82:83], off offset:128
	global_load_dwordx4 v[20:23], v[84:85], off offset:128
	global_load_dwordx4 v[24:27], v[86:87], off offset:128
	global_load_dwordx4 v[32:35], v[88:89], off offset:128
	v_lshlrev_b32_e32 v92, 1, v92
	s_waitcnt vmcnt(15)
	v_cndmask_b32_e64 v28, 0, v28, s[2:3]
	v_cndmask_b32_e64 v29, 0, v29, s[2:3]
	v_cndmask_b32_e64 v30, 0, v30, s[2:3]
	v_cndmask_b32_e64 v31, 0, v31, s[2:3]
	v_lshl_or_b32 v135, v64, 7, v92
	ds_write_b128 v135, v[28:31]
	s_waitcnt vmcnt(14)
	v_cndmask_b32_e64 v28, 0, v36, s[4:5]
	v_cndmask_b32_e64 v29, 0, v37, s[4:5]
	v_cndmask_b32_e64 v30, 0, v38, s[4:5]
	v_cndmask_b32_e64 v31, 0, v39, s[4:5]
	ds_write_b128 v135, v[28:31] offset:4096
	s_waitcnt vmcnt(13)
	v_cndmask_b32_e64 v28, 0, v40, s[6:7]
	v_cndmask_b32_e64 v29, 0, v41, s[6:7]
	v_cndmask_b32_e64 v30, 0, v42, s[6:7]
	v_cndmask_b32_e64 v31, 0, v43, s[6:7]
	ds_write_b128 v135, v[28:31] offset:8192
	s_waitcnt vmcnt(12)
	v_cndmask_b32_e64 v28, 0, v44, s[8:9]
	v_cndmask_b32_e64 v29, 0, v45, s[8:9]
	v_cndmask_b32_e64 v30, 0, v46, s[8:9]
	v_cndmask_b32_e64 v31, 0, v47, s[8:9]
	ds_write_b128 v135, v[28:31] offset:12288
	s_waitcnt vmcnt(11)
	ds_write_b128 v135, v[48:51] offset:36864
	s_waitcnt vmcnt(10)
	ds_write_b128 v135, v[52:55] offset:40960
	s_waitcnt vmcnt(9)
	ds_write_b128 v135, v[56:59] offset:45056
	s_waitcnt vmcnt(8)
	ds_write_b128 v135, v[60:63] offset:49152
	s_waitcnt lgkmcnt(0)
	s_barrier
; template <bool ATRANS = false, bool SWAP = true>
; DEV void gemm_seg(f32x4 (&acc)[4][4], bf16_t* As, bf16_t* Bs, const bf16_t* A, const bf16_t* B, int lda, int ldb,
;                   int K, int arow_lo, int arow_hi) {
;     ...
;   const int so = lrow * LDT + lk;
;   const int sw = lrow * 64 + (((lk >> 3) ^ (lrow & 7)) * 8);
;   const int nk = K / BK;
;   const unsigned am0 = av0 ? 0xffffffffu : 0u, am1 = av1 ? 0xffffffffu : 0u, am2 = av2 ? 0xffffffffu : 0u,
;                  am3 = av3 ? 0xffffffffu : 0u;
;     ...
;   GLOAD(0, 0);
;   GLOAD(1, 1);
;   STAB(0, 0);
;   GLOAD(0, 2);
; DEV void acc_zero(f32x4 (&acc)[4][4]) {
; #pragma unroll
;   for (int m = 0; m < 4; ++m)
; #pragma unroll
;     for (int n = 0; n < 4; ++n) acc[m][n] = f32x4{0.f, 0.f, 0.f, 0.f};
	global_load_dwordx4 v[28:31], v[68:69], off offset:256
	global_load_dwordx4 v[36:39], v[72:73], off offset:256
	global_load_dwordx4 v[40:43], v[76:77], off offset:256
	global_load_dwordx4 v[44:47], v[80:81], off offset:256
	global_load_dwordx4 v[48:51], v[82:83], off offset:256
	global_load_dwordx4 v[52:55], v[84:85], off offset:256
	global_load_dwordx4 v[56:59], v[86:87], off offset:256
	global_load_dwordx4 v[60:63], v[88:89], off offset:256
	v_and_b32_e32 v68, 7, v90
	v_lshlrev_b32_e32 v69, 7, v90
	s_ashr_i32 s35, s34, 31
	v_lshlrev_b32_e32 v64, 6, v90
	v_and_b32_e32 v72, 0x2000, v69
	v_bitop3_b32 v65, v65, v68, 3 bitop3:0x6c
	v_and_b32_e32 v69, 0x780, v69
	s_lshl_b64 s[0:1], s[0:1], 23
	s_lshl_b64 s[22:23], s[34:35], 11
	v_and_b32_e32 v64, 0xffffe000, v64
	v_lshl_or_b32 v65, v65, 4, v69
	s_add_u32 s22, s96, s22
	v_or_b32_e32 v139, v64, v65
	v_or_b32_e32 v164, v72, v65
	v_bitop3_b32 v65, v91, v68, 4 bitop3:0x36
	s_addc_u32 s23, s97, s23
	v_lshl_or_b32 v65, v65, 4, v69
	s_add_u32 s0, s22, s0
	v_or_b32_e32 v165, v64, v65
	s_addc_u32 s1, s23, s1
	v_mov_b32_e32 v64, 0
	v_add_u32_e32 v137, 0xd800, v135
	v_or_b32_e32 v207, v72, v65
	v_lshlrev_b32_e32 v128, 4, v68
	v_lshl_add_u64 v[146:147], s[0:1], 0, v[66:67]
	v_lshl_add_u64 v[148:149], s[0:1], 0, v[70:71]
	v_lshl_add_u64 v[150:151], s[0:1], 0, v[74:75]
	v_lshl_add_u64 v[152:153], s[0:1], 0, v[78:79]
	s_mov_b32 s22, -2
	v_mov_b32_e32 v65, v64
	v_mov_b32_e32 v66, v64
	v_mov_b32_e32 v67, v64
	v_mov_b32_e32 v68, v64
	v_mov_b32_e32 v69, v64
	v_mov_b32_e32 v70, v64
	v_mov_b32_e32 v71, v64
	v_mov_b32_e32 v72, v64
	v_mov_b32_e32 v73, v64
	v_mov_b32_e32 v74, v64
	v_mov_b32_e32 v75, v64
	v_mov_b32_e32 v76, v64
	v_mov_b32_e32 v77, v64
	v_mov_b32_e32 v78, v64
	v_mov_b32_e32 v79, v64
	v_mov_b32_e32 v80, v64
	v_mov_b32_e32 v81, v64
	v_mov_b32_e32 v82, v64
	v_mov_b32_e32 v83, v64
	v_mov_b32_e32 v84, v64
	v_mov_b32_e32 v85, v64
	v_mov_b32_e32 v86, v64
	v_mov_b32_e32 v87, v64
	v_mov_b32_e32 v88, v64
	v_mov_b32_e32 v89, v64
	v_mov_b32_e32 v90, v64
	v_mov_b32_e32 v91, v64
	v_mov_b32_e32 v92, v64
	v_mov_b32_e32 v93, v64
	v_mov_b32_e32 v94, v64
	v_mov_b32_e32 v95, v64
	v_mov_b32_e32 v96, v64
	v_mov_b32_e32 v97, v64
	v_mov_b32_e32 v98, v64
	v_mov_b32_e32 v99, v64
	v_mov_b32_e32 v100, v64
	v_mov_b32_e32 v101, v64
	v_mov_b32_e32 v102, v64
	v_mov_b32_e32 v103, v64
	v_mov_b32_e32 v104, v64
	v_mov_b32_e32 v105, v64
	v_mov_b32_e32 v106, v64
	v_mov_b32_e32 v107, v64
	v_mov_b32_e32 v108, v64
	v_mov_b32_e32 v109, v64
	v_mov_b32_e32 v110, v64
	v_mov_b32_e32 v111, v64
	v_mov_b32_e32 v112, v64
	v_mov_b32_e32 v113, v64
	v_mov_b32_e32 v114, v64
	v_mov_b32_e32 v115, v64
	v_mov_b32_e32 v116, v64
	v_mov_b32_e32 v117, v64
	v_mov_b32_e32 v118, v64
	v_mov_b32_e32 v119, v64
	v_mov_b32_e32 v120, v64
	v_mov_b32_e32 v121, v64
	v_mov_b32_e32 v122, v64
	v_mov_b32_e32 v123, v64
	v_mov_b32_e32 v124, v64
	v_mov_b32_e32 v125, v64
	v_mov_b32_e32 v126, v64
	v_mov_b32_e32 v127, v64
	s_branch .LBB0_824
